# prep: one of the eight prep_b passes of each slow-half workgroup is done by its fast-half partner
# baseline (speedup 1.0000x reference)
.LBB0_1477:
	s_or_b64 exec, exec, s[0:1]
	v_readlane_b32 s24, v254, 0
	s_mov_b32 s98, 0xfffff
	s_cmp_lt_u32 s24, 0x80
	s_cselect_b32 s98, 0xdffff, s98
	s_cselect_b32 s99, 0, 1
	v_mov_b32_e32 v0, v156
	s_barrier
	s_mov_b32 s0, 0x100000
	v_lshl_add_u32 v4, s24, 9, v0
	v_cmp_gt_i32_e32 vcc, s0, v4
	s_and_saveexec_b64 s[0:1], vcc
	s_cbranch_execz .LBB0_1484
	s_add_u32 s4, s48, 0xdca0000
	v_lshlrev_b32_e32 v0, 3, v0
	s_addc_u32 s5, s49, 0
	v_lshl_add_u32 v5, s24, 12, v0
	s_lshl_b32 s31, s92, 12
	s_mov_b64 s[24:25], 0
	s_branch .LBB0_1480
.LBB0_1479:
	s_or_b64 exec, exec, s[28:29]
	v_lshrrev_b32_e32 v6, 10, v144
	v_add_u32_e32 v6, 1, v6
	v_and_b32_e32 v30, 0x3f8, v5
	v_cndmask_b32_e64 v8, v6, 0, vcc
	v_mov_b64_e32 v[6:7], s[46:47]
	s_movk_i32 s28, 0x6000
	v_mad_u64_u32 v[6:7], s[28:29], v8, s28, v[6:7]
	v_lshlrev_b32_e32 v144, 2, v30
	v_lshl_add_u64 v[26:27], v[6:7], 0, v[144:145]
	v_add_co_u32_e32 v6, vcc, s64, v26
	s_mov_b64 s[28:29], 0x1000
	s_nop 0
	v_addc_co_u32_e32 v7, vcc, 0, v27, vcc
	global_load_dwordx4 v[6:9], v[6:7], off
	v_lshl_add_u64 v[10:11], v[26:27], 0, s[28:29]
	v_lshl_add_u64 v[2:3], v[2:3], 0, v[144:145]
	global_load_dwordx4 v[10:13], v[10:11], off offset:16
	s_nop 0
	global_load_dwordx4 v[14:17], v[26:27], off
	global_load_dwordx4 v[18:21], v[2:3], off
	global_load_dwordx4 v[22:25], v[2:3], off offset:16
	s_nop 0
	global_load_dwordx4 v[26:29], v[26:27], off offset:16
	v_lshlrev_b64 v[0:1], 11, v[0:1]
	v_lshl_add_u64 v[0:1], s[4:5], 0, v[0:1]
	v_lshlrev_b32_e32 v144, 1, v30
	v_add_u32_e32 v4, s30, v4
	s_mov_b32 s28, s98
	v_lshl_add_u64 v[30:31], v[0:1], 0, v[144:145]
	v_cmp_lt_i32_e32 vcc, s28, v4
	s_or_b64 s[24:25], vcc, s[24:25]
	v_add_u32_e32 v5, s31, v5
	s_waitcnt vmcnt(5)
	v_pk_add_f32 v[0:1], v[8:9], 1.0 op_sel_hi:[1,0]
	v_pk_add_f32 v[2:3], v[6:7], 1.0 op_sel_hi:[1,0]
	s_waitcnt vmcnt(4)
	v_pk_add_f32 v[6:7], v[12:13], 1.0 op_sel_hi:[1,0]
	v_pk_add_f32 v[8:9], v[10:11], 1.0 op_sel_hi:[1,0]
	s_waitcnt vmcnt(2)
	v_pk_fma_f32 v[10:11], v[20:21], v[0:1], v[16:17]
	v_pk_fma_f32 v[0:1], v[18:19], v[2:3], v[14:15]
	s_waitcnt vmcnt(0)
	v_pk_fma_f32 v[6:7], v[24:25], v[6:7], v[28:29]
	v_pk_fma_f32 v[2:3], v[22:23], v[8:9], v[26:27]
	v_cvt_pk_bf16_f32 v0, v0, v1
	v_cvt_pk_bf16_f32 v1, v10, v11
	v_cvt_pk_bf16_f32 v2, v2, v3
	v_cvt_pk_bf16_f32 v3, v6, v7
	global_store_dwordx4 v[30:31], v[0:3], off
	s_andn2_b64 exec, exec, s[24:25]
	s_cbranch_execz .LBB0_1484

.LBB0_1484:
	s_cmp_eq_u32 s99, 0
	s_cbranch_scc1 .Lpb_done
	s_mov_b32 s99, 0
	s_mov_b32 s98, 0xfffff
	s_mov_b64 exec, s[0:1]
	v_readlane_b32 s24, v254, 0
	v_lshl_add_u32 v4, s24, 9, v156
	v_add_u32_e32 v4, 0xd0000, v4
	s_mov_b64 s[24:25], 0
	s_branch .LBB0_1480
